# plus: RG-LRU unit staging loads (halo tile rows, gate weights) issued together under one wait instead of one round trip per piece
# speedup vs baseline: 1.0110x; 1.0010x over previous
.LBB0_727:
	v_ashrrev_i32_e32 v214, 3, v9
	v_add_u32_e32 v215, s16, v214
	v_mad_u32_u24 v216, v214, s92, v8
	v_mov_b32_e32 v192, 0
	v_mov_b32_e32 v193, 0
	v_mov_b32_e32 v194, 0
	v_mov_b32_e32 v195, 0
	v_cmp_le_i32_e32 vcc, s14, v215
	v_cmp_gt_i32_e64 s[0:1], s15, v215
	s_and_b64 s[18:19], vcc, s[0:1]
	s_and_saveexec_b64 s[0:1], s[18:19]
	v_ashrrev_i32_e32 v213, 31, v215
	v_mov_b32_e32 v212, v215
	v_lshlrev_b64 v[212:213], 12, v[212:213]
	v_lshl_add_u64 v[212:213], v[6:7], 0, v[212:213]
	global_load_dwordx4 v[192:195], v[212:213], off nt
	s_or_b64 exec, exec, s[0:1]
	v_add_u32_e32 v215, 64, v215
	v_mov_b32_e32 v196, 0
	v_mov_b32_e32 v197, 0
	v_mov_b32_e32 v198, 0
	v_mov_b32_e32 v199, 0
	v_cmp_le_i32_e32 vcc, s14, v215
	v_cmp_gt_i32_e64 s[0:1], s15, v215
	s_and_b64 s[18:19], vcc, s[0:1]
	s_and_saveexec_b64 s[0:1], s[18:19]
	v_ashrrev_i32_e32 v213, 31, v215
	v_mov_b32_e32 v212, v215
	v_lshlrev_b64 v[212:213], 12, v[212:213]
	v_lshl_add_u64 v[212:213], v[6:7], 0, v[212:213]
	global_load_dwordx4 v[196:199], v[212:213], off nt
	s_or_b64 exec, exec, s[0:1]
	v_add_u32_e32 v215, 64, v215
	v_mov_b32_e32 v200, 0
	v_mov_b32_e32 v201, 0
	v_mov_b32_e32 v202, 0
	v_mov_b32_e32 v203, 0
	v_cmp_le_i32_e32 vcc, s14, v215
	v_cmp_gt_i32_e64 s[0:1], s15, v215
	s_and_b64 s[18:19], vcc, s[0:1]
	s_and_saveexec_b64 s[0:1], s[18:19]
	v_ashrrev_i32_e32 v213, 31, v215
	v_mov_b32_e32 v212, v215
	v_lshlrev_b64 v[212:213], 12, v[212:213]
	v_lshl_add_u64 v[212:213], v[6:7], 0, v[212:213]
	global_load_dwordx4 v[200:203], v[212:213], off nt
	s_or_b64 exec, exec, s[0:1]
	v_add_u32_e32 v215, 64, v215
	v_mov_b32_e32 v204, 0
	v_mov_b32_e32 v205, 0
	v_mov_b32_e32 v206, 0
	v_mov_b32_e32 v207, 0
	v_cmp_le_i32_e32 vcc, s14, v215
	v_cmp_gt_i32_e64 s[0:1], s15, v215
	s_and_b64 s[18:19], vcc, s[0:1]
	s_and_saveexec_b64 s[0:1], s[18:19]
	v_ashrrev_i32_e32 v213, 31, v215
	v_mov_b32_e32 v212, v215
	v_lshlrev_b64 v[212:213], 12, v[212:213]
	v_lshl_add_u64 v[212:213], v[6:7], 0, v[212:213]
	global_load_dwordx4 v[204:207], v[212:213], off nt
	s_or_b64 exec, exec, s[0:1]
	v_add_u32_e32 v215, 64, v215
	v_mov_b32_e32 v208, 0
	v_mov_b32_e32 v209, 0
	v_mov_b32_e32 v210, 0
	v_mov_b32_e32 v211, 0
	v_cmp_gt_i32_e32 vcc, 32, v9
	s_and_saveexec_b64 s[10:11], vcc
	v_cmp_le_i32_e32 vcc, s14, v215
	v_cmp_gt_i32_e64 s[0:1], s15, v215
	s_and_b64 s[18:19], vcc, s[0:1]
	s_and_saveexec_b64 s[0:1], s[18:19]
	v_ashrrev_i32_e32 v213, 31, v215
	v_mov_b32_e32 v212, v215
	v_lshlrev_b64 v[212:213], 12, v[212:213]
	v_lshl_add_u64 v[212:213], v[6:7], 0, v[212:213]
	global_load_dwordx4 v[208:211], v[212:213], off nt
	s_or_b64 exec, exec, s[0:1]
	s_or_b64 exec, exec, s[10:11]
.LBB0_729:
	s_or_b64 exec, exec, s[6:7]
	s_and_b64 vcc, exec, s[4:5]
	v_add_u32_e32 v24, 0x200, v22
	s_cbranch_vccz .Lstg_nowt
	s_lshl_b32 s0, s17, 15
	v_readlane_b32 s1, v254, 30
	s_or_b32 s0, s0, s1
	s_add_u32 s0, s2, s0
	s_addc_u32 s1, s3, 0
	v_lshl_add_u64 v[2:3], s[0:1], 0, v[0:1]
	s_mov_b64 s[0:1], 0x55c4100
	v_ashrrev_i32_e32 v8, 3, v22
	v_lshl_add_u64 v[6:7], v[2:3], 0, s[0:1]
	v_lshlrev_b32_e32 v2, 6, v8
	v_ashrrev_i32_e32 v3, 31, v2
	v_lshl_add_u64 v[2:3], v[2:3], 1, v[6:7]
	global_load_dwordx4 v[224:227], v[2:3], off
	v_add_u32_e32 v0, s52, v0
	v_mad_u64_u32 v[240:241], s[0:1], v8, s92, v[0:1]
	v_ashrrev_i32_e32 v8, 3, v24
	v_lshlrev_b32_e32 v2, 6, v8
	v_ashrrev_i32_e32 v3, 31, v2
	v_lshl_add_u64 v[2:3], v[2:3], 1, v[6:7]
	global_load_dwordx4 v[228:231], v[2:3], off
	v_mad_u64_u32 v[242:243], s[0:1], v8, s92, v[0:1]
	v_add_u32_e32 v2, 0x400, v22
	v_ashrrev_i32_e32 v8, 3, v2
	v_lshlrev_b32_e32 v2, 6, v8
	v_ashrrev_i32_e32 v3, 31, v2
	v_lshl_add_u64 v[2:3], v[2:3], 1, v[6:7]
	global_load_dwordx4 v[232:235], v[2:3], off
	v_mad_u64_u32 v[244:245], s[0:1], v8, s92, v[0:1]
	v_add_u32_e32 v2, 0x600, v22
	v_ashrrev_i32_e32 v8, 3, v2
	v_lshlrev_b32_e32 v2, 6, v8
	v_ashrrev_i32_e32 v3, 31, v2
	v_lshl_add_u64 v[2:3], v[2:3], 1, v[6:7]
	global_load_dwordx4 v[236:239], v[2:3], off
	v_mad_u64_u32 v[6:7], s[0:1], v8, s92, v[0:1]
.Lstg_nowt:
	s_waitcnt vmcnt(0)
	ds_write_b128 v216, v[192:195]
	ds_write_b128 v216, v[196:199] offset:9216
	ds_write_b128 v216, v[200:203] offset:18432
	ds_write_b128 v216, v[204:207] offset:27648
	v_cmp_gt_i32_e32 vcc, 32, v22
	s_and_saveexec_b64 s[10:11], vcc
	ds_write_b128 v216, v[208:211] offset:36864
	s_or_b64 exec, exec, s[10:11]
	s_and_b64 vcc, exec, s[4:5]
	s_cbranch_vccz .LBB0_731
	ds_write_b128 v240, v[224:227]
	ds_write_b128 v242, v[228:231]
	ds_write_b128 v244, v[232:235]
	ds_write_b128 v6, v[236:239]
